# conv phase: activation pair-row staging issues all of a wave's row loads up front (static count, clamped) before interleaving and writing them to LDS, instead of one memory round trip per pair-row
# baseline (speedup 1.0000x reference)
; #define LAS __attribute__((address_space(3)))
; DI u32x4 pk8(f32x4 a, f32x4 b) { u32x4 w; w.x = pk2(a[0], a[1]); w.y = pk2(a[2], a[3]); w.z = pk2(b[0], b[1]); w.w = pk2(b[2], b[3]); return w; }
; DI void phase_conv(const Params& p, LAS unsigned char* lds) {
;     ...
;         for (int pr_ = wid; pr_ < (R + 30) / 2; pr_ += 8) {
;             u32x4 v0 = (u32x4){0u, 0u, 0u, 0u}, v1 = v0;
;             const int ta = t0 - 30 + 2 * pr_;
;             if (ta >= 0) { v0 = *(const u32x4*)(A0 + (rowbase + ta) * MW + c0); v1 = *(const u32x4*)(A0 + (rowbase + ta + 1) * MW + c0); }
;             else if (samp) { const f32x4* s0 = (const f32x4*)(cache_a + ((size_t)b * 30 + (30 + ta)) * MW + c0); const f32x4* s1 = s0 + MW / 4; v0 = pk8(s0[0], s0[1]); v1 = pk8(s1[0], s1[1]); }
;             u32x4 e0, e1;
;             e0.x = (v0.x & 0xffffu) | (v1.x << 16); e0.y = (v0.x >> 16) | (v1.x & 0xffff0000u); e0.z = (v0.y & 0xffffu) | (v1.y << 16); e0.w = (v0.y >> 16) | (v1.y & 0xffff0000u);
;             e1.x = (v0.z & 0xffffu) | (v1.z << 16); e1.y = (v0.z >> 16) | (v1.z & 0xffff0000u); e1.z = (v0.w & 0xffffu) | (v1.w << 16); e1.w = (v0.w >> 16) | (v1.w & 0xffff0000u);
;             *(LAS u32x4*)(lds + pr_ * 2048 + lane * 16) = e0; *(LAS u32x4*)(lds + pr_ * 2048 + 1024 + lane * 16) = e1;
;         }
.LBB0_415:
	s_mul_hi_u32 s69, s76, 0xf000
	s_andn2_b64 vcc, exec, s[0:1]
	s_mul_i32 s68, s76, 0xf000
	s_cbranch_vccnz .LBB0_424
	v_lshl_add_u64 v[10:11], v[42:43], 0, s[68:69]
	s_add_i32 s79, s33, s72
	v_mov_b32_e32 v12, v187
	s_mov_b32 s89, s8
	s_cmp_lt_i32 s79, 0
	s_cbranch_scc1 .LBB0_418
	s_sub_i32 s98, s78, s89
	s_add_i32 s98, s98, -1
	s_lshr_b32 s98, s98, 3
	s_lshl_b32 s99, s98, 4
	s_add_i32 s99, s99, s79
	s_mov_b32 s100, s79
	s_add_u32 s0, s62, s100
	s_addc_u32 s1, s63, 0
	s_lshl_b64 s[0:1], s[0:1], 10
	v_lshl_add_u64 v[18:19], v[38:39], 0, s[0:1]
	global_load_dwordx4 v[216:219], v[18:19], off
	global_load_dwordx4 v[220:223], v[18:19], off offset:1024
	s_add_i32 s100, s79, 16
	s_min_i32 s100, s100, s99
	s_add_u32 s0, s62, s100
	s_addc_u32 s1, s63, 0
	s_lshl_b64 s[0:1], s[0:1], 10
	v_lshl_add_u64 v[18:19], v[38:39], 0, s[0:1]
	global_load_dwordx4 v[224:227], v[18:19], off
	global_load_dwordx4 v[228:231], v[18:19], off offset:1024
	s_add_i32 s100, s79, 32
	s_min_i32 s100, s100, s99
	s_add_u32 s0, s62, s100
	s_addc_u32 s1, s63, 0
	s_lshl_b64 s[0:1], s[0:1], 10
	v_lshl_add_u64 v[18:19], v[38:39], 0, s[0:1]
	global_load_dwordx4 v[232:235], v[18:19], off
	global_load_dwordx4 v[236:239], v[18:19], off offset:1024
	s_add_i32 s100, s79, 48
	s_min_i32 s100, s100, s99
	s_add_u32 s0, s62, s100
	s_addc_u32 s1, s63, 0
	s_lshl_b64 s[0:1], s[0:1], 10
	v_lshl_add_u64 v[18:19], v[38:39], 0, s[0:1]
	global_load_dwordx4 v[240:243], v[18:19], off
	global_load_dwordx4 v[248:251], v[18:19], off offset:1024
	s_add_i32 s100, s79, 64
	s_min_i32 s100, s100, s99
	s_add_u32 s0, s62, s100
	s_addc_u32 s1, s63, 0
	s_lshl_b64 s[0:1], s[0:1], 10
	v_lshl_add_u64 v[18:19], v[38:39], 0, s[0:1]
	global_load_dwordx4 v[252:255], v[18:19], off
	global_load_dwordx4 v[2:5], v[18:19], off offset:1024
	s_add_i32 s100, s79, 80
	s_min_i32 s100, s100, s99
	s_add_u32 s0, s62, s100
	s_addc_u32 s1, s63, 0
	s_lshl_b64 s[0:1], s[0:1], 10
	v_lshl_add_u64 v[18:19], v[38:39], 0, s[0:1]
	global_load_dwordx4 v[6:9], v[18:19], off
	global_load_dwordx4 v[190:193], v[18:19], off offset:1024
	s_waitcnt vmcnt(10)
	v_lshlrev_b32_e32 v13, 16, v220
	v_and_or_b32 v14, v216, s85, v13
	v_lshrrev_b32_e32 v13, 16, v216
	v_and_or_b32 v15, v220, s86, v13
	v_lshlrev_b32_e32 v13, 16, v221
	v_and_or_b32 v16, v217, s85, v13
	v_lshrrev_b32_e32 v13, 16, v217
	v_and_or_b32 v17, v221, s86, v13
	v_lshlrev_b32_e32 v13, 16, v222
	v_and_or_b32 v20, v218, s85, v13
	v_lshrrev_b32_e32 v13, 16, v218
	v_and_or_b32 v21, v222, s86, v13
	v_lshlrev_b32_e32 v13, 16, v223
	v_and_or_b32 v22, v219, s85, v13
	v_lshrrev_b32_e32 v13, 16, v219
	v_and_or_b32 v23, v223, s86, v13
	ds_write_b128 v12, v[14:17]
	ds_write_b128 v12, v[20:23] offset:1024
	v_add_u32_e32 v12, 0x4000, v12
	s_cmp_eq_u32 s98, 0
	s_cbranch_scc1 .Lmy_cs_done
	s_waitcnt vmcnt(8)
	v_lshlrev_b32_e32 v13, 16, v228
	v_and_or_b32 v14, v224, s85, v13
	v_lshrrev_b32_e32 v13, 16, v224
	v_and_or_b32 v15, v228, s86, v13
	v_lshlrev_b32_e32 v13, 16, v229
	v_and_or_b32 v16, v225, s85, v13
	v_lshrrev_b32_e32 v13, 16, v225
	v_and_or_b32 v17, v229, s86, v13
	v_lshlrev_b32_e32 v13, 16, v230
	v_and_or_b32 v20, v226, s85, v13
	v_lshrrev_b32_e32 v13, 16, v226
	v_and_or_b32 v21, v230, s86, v13
	v_lshlrev_b32_e32 v13, 16, v231
	v_and_or_b32 v22, v227, s85, v13
	v_lshrrev_b32_e32 v13, 16, v227
	v_and_or_b32 v23, v231, s86, v13
	ds_write_b128 v12, v[14:17]
	ds_write_b128 v12, v[20:23] offset:1024
	v_add_u32_e32 v12, 0x4000, v12
	s_cmp_eq_u32 s98, 1
	s_cbranch_scc1 .Lmy_cs_done
	s_waitcnt vmcnt(6)
	v_lshlrev_b32_e32 v13, 16, v236
	v_and_or_b32 v14, v232, s85, v13
	v_lshrrev_b32_e32 v13, 16, v232
	v_and_or_b32 v15, v236, s86, v13
	v_lshlrev_b32_e32 v13, 16, v237
	v_and_or_b32 v16, v233, s85, v13
	v_lshrrev_b32_e32 v13, 16, v233
	v_and_or_b32 v17, v237, s86, v13
	v_lshlrev_b32_e32 v13, 16, v238
	v_and_or_b32 v20, v234, s85, v13
	v_lshrrev_b32_e32 v13, 16, v234
	v_and_or_b32 v21, v238, s86, v13
	v_lshlrev_b32_e32 v13, 16, v239
	v_and_or_b32 v22, v235, s85, v13
	v_lshrrev_b32_e32 v13, 16, v235
	v_and_or_b32 v23, v239, s86, v13
	ds_write_b128 v12, v[14:17]
	ds_write_b128 v12, v[20:23] offset:1024
	v_add_u32_e32 v12, 0x4000, v12
	s_cmp_eq_u32 s98, 2
	s_cbranch_scc1 .Lmy_cs_done
	s_waitcnt vmcnt(4)
	v_lshlrev_b32_e32 v13, 16, v248
	v_and_or_b32 v14, v240, s85, v13
	v_lshrrev_b32_e32 v13, 16, v240
	v_and_or_b32 v15, v248, s86, v13
	v_lshlrev_b32_e32 v13, 16, v249
	v_and_or_b32 v16, v241, s85, v13
	v_lshrrev_b32_e32 v13, 16, v241
	v_and_or_b32 v17, v249, s86, v13
	v_lshlrev_b32_e32 v13, 16, v250
	v_and_or_b32 v20, v242, s85, v13
	v_lshrrev_b32_e32 v13, 16, v242
	v_and_or_b32 v21, v250, s86, v13
	v_lshlrev_b32_e32 v13, 16, v251
	v_and_or_b32 v22, v243, s85, v13
	v_lshrrev_b32_e32 v13, 16, v243
	v_and_or_b32 v23, v251, s86, v13
	ds_write_b128 v12, v[14:17]
	ds_write_b128 v12, v[20:23] offset:1024
	v_add_u32_e32 v12, 0x4000, v12
	s_cmp_eq_u32 s98, 3
	s_cbranch_scc1 .Lmy_cs_done
	s_waitcnt vmcnt(2)
	v_lshlrev_b32_e32 v13, 16, v2
	v_and_or_b32 v14, v252, s85, v13
	v_lshrrev_b32_e32 v13, 16, v252
	v_and_or_b32 v15, v2, s86, v13
	v_lshlrev_b32_e32 v13, 16, v3
	v_and_or_b32 v16, v253, s85, v13
	v_lshrrev_b32_e32 v13, 16, v253
	v_and_or_b32 v17, v3, s86, v13
	v_lshlrev_b32_e32 v13, 16, v4
	v_and_or_b32 v20, v254, s85, v13
	v_lshrrev_b32_e32 v13, 16, v254
	v_and_or_b32 v21, v4, s86, v13
	v_lshlrev_b32_e32 v13, 16, v5
	v_and_or_b32 v22, v255, s85, v13
	v_lshrrev_b32_e32 v13, 16, v255
	v_and_or_b32 v23, v5, s86, v13
	ds_write_b128 v12, v[14:17]
	ds_write_b128 v12, v[20:23] offset:1024
	v_add_u32_e32 v12, 0x4000, v12
	s_cmp_eq_u32 s98, 4
	s_cbranch_scc1 .Lmy_cs_done
	s_waitcnt vmcnt(0)
	v_lshlrev_b32_e32 v13, 16, v190
	v_and_or_b32 v14, v6, s85, v13
	v_lshrrev_b32_e32 v13, 16, v6
	v_and_or_b32 v15, v190, s86, v13
	v_lshlrev_b32_e32 v13, 16, v191
	v_and_or_b32 v16, v7, s85, v13
	v_lshrrev_b32_e32 v13, 16, v7
	v_and_or_b32 v17, v191, s86, v13
	v_lshlrev_b32_e32 v13, 16, v192
	v_and_or_b32 v20, v8, s85, v13
	v_lshrrev_b32_e32 v13, 16, v8
	v_and_or_b32 v21, v192, s86, v13
	v_lshlrev_b32_e32 v13, 16, v193
	v_and_or_b32 v22, v9, s85, v13
	v_lshrrev_b32_e32 v13, 16, v9
	v_and_or_b32 v23, v193, s86, v13
	ds_write_b128 v12, v[14:17]
	ds_write_b128 v12, v[20:23] offset:1024
.Lmy_cs_done:
	s_branch .LBB0_424
.LBB0_417:
	s_waitcnt vmcnt(0)
	v_lshlrev_b32_e32 v13, 16, v6
	v_and_or_b32 v14, v2, s85, v13
	v_lshrrev_b32_e32 v2, 16, v2
	v_and_or_b32 v15, v6, s86, v2
	v_lshlrev_b32_e32 v2, 16, v7
	v_and_or_b32 v16, v3, s85, v2
	v_lshrrev_b32_e32 v2, 16, v3
	v_and_or_b32 v17, v7, s86, v2
	v_lshlrev_b32_e32 v2, 16, v8
	v_and_or_b32 v2, v4, s85, v2
	v_lshrrev_b32_e32 v3, 16, v4
	v_lshlrev_b32_e32 v4, 16, v9
	v_and_or_b32 v4, v5, s85, v4
	v_lshrrev_b32_e32 v5, 16, v5
	s_add_i32 s89, s89, 8
	s_add_i32 s79, s79, 16
	v_and_or_b32 v3, v8, s86, v3
	v_and_or_b32 v5, v9, s86, v5
	ds_write_b128 v12, v[14:17]
	ds_write_b128 v12, v[2:5] offset:1024
	v_add_u32_e32 v12, 0x4000, v12
	s_cmp_ge_u32 s89, s78
	v_lshl_add_u64 v[10:11], v[10:11], 0, s[16:17]
	s_cbranch_scc1 .LBB0_424
